# v20 + hgrn_m3: the next chunk's Tl row is published before the chunk's last barrier, which then doubles as the next chunk's first barrier (one barrier per chunk fewer)
# baseline (speedup 1.0000x reference)
; __device__ __forceinline__ unsigned pk2(float lo, float hi) { return cvt_pk_bf16(lo, hi); }
; __device__ __forceinline__ void hgrn_m2(Frame& F) {
;     ...
;         bf16* p = RS + (size_t)bh * 4 * 16384 + e0; const float* dp = RD + (size_t)bh * 4 * 128 + k0;
; #pragma unroll
;         for (int c = 0; c < 4; ++c) {
;             const u32x4 u = *(const u32x4*)(p + (size_t)c * 16384);
;             const f32x4 d0 = *(const f32x4*)(dp + c * 128), d1 = *(const f32x4*)(dp + c * 128 + 4);
;             u32x4 o; o.x = pk2(S[0], S[1]); o.y = pk2(S[2], S[3]); o.z = pk2(S[4], S[5]); o.w = pk2(S[6], S[7]);
;             *(u32x4*)(p + (size_t)c * 16384) = o;
;             S[0] = d0[0] * S[0] + bflo(u.x); S[1] = d0[1] * S[1] + bfhi(u.x); S[2] = d0[2] * S[2] + bflo(u.y); S[3] = d0[3] * S[3] + bfhi(u.y);
;             S[4] = d1[0] * S[4] + bflo(u.z); S[5] = d1[1] * S[5] + bfhi(u.z); S[6] = d1[2] * S[6] + bflo(u.w); S[7] = d1[3] * S[7] + bfhi(u.w);
;         }
; __device__ __forceinline__ void hgrn_m3(Frame& F) {
;     ...
;     for (int rg = F.bx; rg < 256; rg += F.G) {
;       f32x16 st[2];
; #pragma unroll
;       for (int x = 0; x < 2; ++x)
; #pragma unroll
;           for (int g4 = 0; g4 < 4; ++g4) { const u32x2 w = *(const u32x2*)(RS + (size_t)rg * 16384 + (size_t)(32 * (vt0 + x) + r32) * 128 + 32 * kt + 8 * g4 + 4 * hi5);
;               st[x][4 * g4] = bflo(w.x); st[x][4 * g4 + 1] = bfhi(w.x); st[x][4 * g4 + 2] = bflo(w.y); st[x][4 * g4 + 3] = bfhi(w.y); }
.LBB0_443:
	s_mov_b32 s101, 0
	s_and_b32 s1, s0, 3
	s_sub_i32 s24, s0, s1
	s_lshl_b32 s12, s24, 9
	s_lshl_b32 s24, s24, 15
	v_readlane_b32 s7, v255, 19
	v_readlane_b32 s16, v255, 20
	s_add_u32 s24, s7, s24
	s_addc_u32 s25, s16, 0
	s_add_u32 s24, s24, 0x4900000
	s_addc_u32 s25, s25, 0
	s_add_u32 s12, s7, s12
	s_addc_u32 s13, s16, 0
	s_add_u32 s12, s12, 0x5100000
	s_addc_u32 s13, s13, 0
	v_and_b32_e32 v68, 31, v0
	v_lshlrev_b32_e32 v68, 8, v68
	v_bfe_u32 v69, v0, 6, 1
	v_lshl_add_u32 v68, v69, 14, v68
	v_lshl_add_u32 v68, v72, 6, v68
	v_bfe_u32 v69, v0, 5, 1
	v_lshl_add_u32 v68, v69, 3, v68
	v_add_u32_e32 v70, 0x2000, v68
	v_lshlrev_b32_e32 v69, 4, v69
	v_lshl_add_u32 v69, v72, 7, v69
	s_cmp_eq_u32 s1, 0
	s_cbranch_scc1 .Lmy_m3_s0
	global_load_dwordx2 v[34:35], v68, s[24:25]
	global_load_dwordx2 v[36:37], v68, s[24:25] offset:16
	global_load_dwordx2 v[38:39], v68, s[24:25] offset:32
	global_load_dwordx2 v[40:41], v68, s[24:25] offset:48
	global_load_dwordx2 v[42:43], v70, s[24:25]
	global_load_dwordx2 v[44:45], v70, s[24:25] offset:16
	global_load_dwordx2 v[46:47], v70, s[24:25] offset:32
	global_load_dwordx2 v[48:49], v70, s[24:25] offset:48
	s_waitcnt vmcnt(0)
	v_lshlrev_b32_e32 v2, 16, v34
	v_and_b32_e32 v3, 0xffff0000, v34
	v_lshlrev_b32_e32 v4, 16, v35
	v_and_b32_e32 v5, 0xffff0000, v35
	v_lshlrev_b32_e32 v6, 16, v36
	v_and_b32_e32 v7, 0xffff0000, v36
	v_lshlrev_b32_e32 v8, 16, v37
	v_and_b32_e32 v9, 0xffff0000, v37
	v_lshlrev_b32_e32 v10, 16, v38
	v_and_b32_e32 v11, 0xffff0000, v38
	v_lshlrev_b32_e32 v12, 16, v39
	v_and_b32_e32 v13, 0xffff0000, v39
	v_lshlrev_b32_e32 v14, 16, v40
	v_and_b32_e32 v15, 0xffff0000, v40
	v_lshlrev_b32_e32 v16, 16, v41
	v_and_b32_e32 v17, 0xffff0000, v41
	v_lshlrev_b32_e32 v18, 16, v42
	v_and_b32_e32 v19, 0xffff0000, v42
	v_lshlrev_b32_e32 v20, 16, v43
	v_and_b32_e32 v21, 0xffff0000, v43
	v_lshlrev_b32_e32 v22, 16, v44
	v_and_b32_e32 v23, 0xffff0000, v44
	v_lshlrev_b32_e32 v24, 16, v45
	v_and_b32_e32 v25, 0xffff0000, v45
	v_lshlrev_b32_e32 v26, 16, v46
	v_and_b32_e32 v27, 0xffff0000, v46
	v_lshlrev_b32_e32 v28, 16, v47
	v_and_b32_e32 v29, 0xffff0000, v47
	v_lshlrev_b32_e32 v30, 16, v48
	v_and_b32_e32 v31, 0xffff0000, v48
	v_lshlrev_b32_e32 v32, 16, v49
	v_and_b32_e32 v33, 0xffff0000, v49
	v_add_f32_e32 v2, 0, v2
	v_add_f32_e32 v3, 0, v3
	v_add_f32_e32 v4, 0, v4
	v_add_f32_e32 v5, 0, v5
	v_add_f32_e32 v6, 0, v6
	v_add_f32_e32 v7, 0, v7
	v_add_f32_e32 v8, 0, v8
	v_add_f32_e32 v9, 0, v9
	v_add_f32_e32 v10, 0, v10
	v_add_f32_e32 v11, 0, v11
	v_add_f32_e32 v12, 0, v12
	v_add_f32_e32 v13, 0, v13
	v_add_f32_e32 v14, 0, v14
	v_add_f32_e32 v15, 0, v15
	v_add_f32_e32 v16, 0, v16
	v_add_f32_e32 v17, 0, v17
	v_add_f32_e32 v18, 0, v18
	v_add_f32_e32 v19, 0, v19
	v_add_f32_e32 v20, 0, v20
	v_add_f32_e32 v21, 0, v21
	v_add_f32_e32 v22, 0, v22
	v_add_f32_e32 v23, 0, v23
	v_add_f32_e32 v24, 0, v24
	v_add_f32_e32 v25, 0, v25
	v_add_f32_e32 v26, 0, v26
	v_add_f32_e32 v27, 0, v27
	v_add_f32_e32 v28, 0, v28
	v_add_f32_e32 v29, 0, v29
	v_add_f32_e32 v30, 0, v30
	v_add_f32_e32 v31, 0, v31
	v_add_f32_e32 v32, 0, v32
	v_add_f32_e32 v33, 0, v33
	s_cmp_eq_u32 s1, 1
	s_cbranch_scc1 .Lmy_m3_round
; __device__ __forceinline__ unsigned pk2(float lo, float hi) { return cvt_pk_bf16(lo, hi); }
; __device__ __forceinline__ void hgrn_m2(Frame& F) {
;     ...
;         bf16* p = RS + (size_t)bh * 4 * 16384 + e0; const float* dp = RD + (size_t)bh * 4 * 128 + k0;
; #pragma unroll
;         for (int c = 0; c < 4; ++c) {
;             const u32x4 u = *(const u32x4*)(p + (size_t)c * 16384);
;             const f32x4 d0 = *(const f32x4*)(dp + c * 128), d1 = *(const f32x4*)(dp + c * 128 + 4);
;             u32x4 o; o.x = pk2(S[0], S[1]); o.y = pk2(S[2], S[3]); o.z = pk2(S[4], S[5]); o.w = pk2(S[6], S[7]);
;             *(u32x4*)(p + (size_t)c * 16384) = o;
;             S[0] = d0[0] * S[0] + bflo(u.x); S[1] = d0[1] * S[1] + bfhi(u.x); S[2] = d0[2] * S[2] + bflo(u.y); S[3] = d0[3] * S[3] + bfhi(u.y);
;             S[4] = d1[0] * S[4] + bflo(u.z); S[5] = d1[1] * S[5] + bfhi(u.z); S[6] = d1[2] * S[6] + bflo(u.w); S[7] = d1[3] * S[7] + bfhi(u.w);
;         }
	s_add_u32 s24, s24, 0x8000
	s_addc_u32 s25, s25, 0
	s_add_u32 s12, s12, 0x200
	s_addc_u32 s13, s13, 0
	global_load_dwordx2 v[34:35], v68, s[24:25]
	global_load_dwordx2 v[36:37], v68, s[24:25] offset:16
	global_load_dwordx2 v[38:39], v68, s[24:25] offset:32
	global_load_dwordx2 v[40:41], v68, s[24:25] offset:48
	global_load_dwordx2 v[42:43], v70, s[24:25]
	global_load_dwordx2 v[44:45], v70, s[24:25] offset:16
	global_load_dwordx2 v[46:47], v70, s[24:25] offset:32
	global_load_dwordx2 v[48:49], v70, s[24:25] offset:48
	global_load_dwordx4 v[50:53], v69, s[12:13]
	global_load_dwordx4 v[54:57], v69, s[12:13] offset:32
	global_load_dwordx4 v[58:61], v69, s[12:13] offset:64
	global_load_dwordx4 v[62:65], v69, s[12:13] offset:96
	s_waitcnt vmcnt(0)
	v_lshlrev_b32_e32 v71, 16, v34
	v_fma_f32 v2, v2, v50, v71
	v_and_b32_e32 v71, 0xffff0000, v34
	v_fma_f32 v3, v3, v51, v71
	v_lshlrev_b32_e32 v71, 16, v35
	v_fma_f32 v4, v4, v52, v71
	v_and_b32_e32 v71, 0xffff0000, v35
	v_fma_f32 v5, v5, v53, v71
	v_lshlrev_b32_e32 v71, 16, v36
	v_fma_f32 v6, v6, v54, v71
	v_and_b32_e32 v71, 0xffff0000, v36
	v_fma_f32 v7, v7, v55, v71
	v_lshlrev_b32_e32 v71, 16, v37
	v_fma_f32 v8, v8, v56, v71
	v_and_b32_e32 v71, 0xffff0000, v37
	v_fma_f32 v9, v9, v57, v71
	v_lshlrev_b32_e32 v71, 16, v38
	v_fma_f32 v10, v10, v58, v71
	v_and_b32_e32 v71, 0xffff0000, v38
	v_fma_f32 v11, v11, v59, v71
	v_lshlrev_b32_e32 v71, 16, v39
	v_fma_f32 v12, v12, v60, v71
	v_and_b32_e32 v71, 0xffff0000, v39
	v_fma_f32 v13, v13, v61, v71
	v_lshlrev_b32_e32 v71, 16, v40
	v_fma_f32 v14, v14, v62, v71
	v_and_b32_e32 v71, 0xffff0000, v40
	v_fma_f32 v15, v15, v63, v71
	v_lshlrev_b32_e32 v71, 16, v41
	v_fma_f32 v16, v16, v64, v71
	v_and_b32_e32 v71, 0xffff0000, v41
	v_fma_f32 v17, v17, v65, v71
	v_lshlrev_b32_e32 v71, 16, v42
	v_fma_f32 v18, v18, v50, v71
	v_and_b32_e32 v71, 0xffff0000, v42
	v_fma_f32 v19, v19, v51, v71
	v_lshlrev_b32_e32 v71, 16, v43
	v_fma_f32 v20, v20, v52, v71
	v_and_b32_e32 v71, 0xffff0000, v43
	v_fma_f32 v21, v21, v53, v71
	v_lshlrev_b32_e32 v71, 16, v44
	v_fma_f32 v22, v22, v54, v71
	v_and_b32_e32 v71, 0xffff0000, v44
	v_fma_f32 v23, v23, v55, v71
	v_lshlrev_b32_e32 v71, 16, v45
	v_fma_f32 v24, v24, v56, v71
	v_and_b32_e32 v71, 0xffff0000, v45
	v_fma_f32 v25, v25, v57, v71
	v_lshlrev_b32_e32 v71, 16, v46
	v_fma_f32 v26, v26, v58, v71
	v_and_b32_e32 v71, 0xffff0000, v46
	v_fma_f32 v27, v27, v59, v71
	v_lshlrev_b32_e32 v71, 16, v47
	v_fma_f32 v28, v28, v60, v71
	v_and_b32_e32 v71, 0xffff0000, v47
	v_fma_f32 v29, v29, v61, v71
	v_lshlrev_b32_e32 v71, 16, v48
	v_fma_f32 v30, v30, v62, v71
	v_and_b32_e32 v71, 0xffff0000, v48
	v_fma_f32 v31, v31, v63, v71
	v_lshlrev_b32_e32 v71, 16, v49
	v_fma_f32 v32, v32, v64, v71
	v_and_b32_e32 v71, 0xffff0000, v49
	v_fma_f32 v33, v33, v65, v71
	s_cmp_eq_u32 s1, 2
	s_cbranch_scc1 .Lmy_m3_round
	s_add_u32 s24, s24, 0x8000
	s_addc_u32 s25, s25, 0
	s_add_u32 s12, s12, 0x200
	s_addc_u32 s13, s13, 0
	global_load_dwordx2 v[34:35], v68, s[24:25]
	global_load_dwordx2 v[36:37], v68, s[24:25] offset:16
	global_load_dwordx2 v[38:39], v68, s[24:25] offset:32
	global_load_dwordx2 v[40:41], v68, s[24:25] offset:48
	global_load_dwordx2 v[42:43], v70, s[24:25]
	global_load_dwordx2 v[44:45], v70, s[24:25] offset:16
	global_load_dwordx2 v[46:47], v70, s[24:25] offset:32
	global_load_dwordx2 v[48:49], v70, s[24:25] offset:48
	global_load_dwordx4 v[50:53], v69, s[12:13]
	global_load_dwordx4 v[54:57], v69, s[12:13] offset:32
	global_load_dwordx4 v[58:61], v69, s[12:13] offset:64
	global_load_dwordx4 v[62:65], v69, s[12:13] offset:96
	s_waitcnt vmcnt(0)
	v_lshlrev_b32_e32 v71, 16, v34
	v_fma_f32 v2, v2, v50, v71
	v_and_b32_e32 v71, 0xffff0000, v34
	v_fma_f32 v3, v3, v51, v71
	v_lshlrev_b32_e32 v71, 16, v35
	v_fma_f32 v4, v4, v52, v71
	v_and_b32_e32 v71, 0xffff0000, v35
	v_fma_f32 v5, v5, v53, v71
	v_lshlrev_b32_e32 v71, 16, v36
	v_fma_f32 v6, v6, v54, v71
	v_and_b32_e32 v71, 0xffff0000, v36
	v_fma_f32 v7, v7, v55, v71
	v_lshlrev_b32_e32 v71, 16, v37
	v_fma_f32 v8, v8, v56, v71
	v_and_b32_e32 v71, 0xffff0000, v37
	v_fma_f32 v9, v9, v57, v71
	v_lshlrev_b32_e32 v71, 16, v38
	v_fma_f32 v10, v10, v58, v71
	v_and_b32_e32 v71, 0xffff0000, v38
	v_fma_f32 v11, v11, v59, v71
	v_lshlrev_b32_e32 v71, 16, v39
	v_fma_f32 v12, v12, v60, v71
	v_and_b32_e32 v71, 0xffff0000, v39
	v_fma_f32 v13, v13, v61, v71
	v_lshlrev_b32_e32 v71, 16, v40
	v_fma_f32 v14, v14, v62, v71
	v_and_b32_e32 v71, 0xffff0000, v40
	v_fma_f32 v15, v15, v63, v71
	v_lshlrev_b32_e32 v71, 16, v41
	v_fma_f32 v16, v16, v64, v71
	v_and_b32_e32 v71, 0xffff0000, v41
	v_fma_f32 v17, v17, v65, v71
	v_lshlrev_b32_e32 v71, 16, v42
	v_fma_f32 v18, v18, v50, v71
	v_and_b32_e32 v71, 0xffff0000, v42
	v_fma_f32 v19, v19, v51, v71
	v_lshlrev_b32_e32 v71, 16, v43
	v_fma_f32 v20, v20, v52, v71
	v_and_b32_e32 v71, 0xffff0000, v43
	v_fma_f32 v21, v21, v53, v71
	v_lshlrev_b32_e32 v71, 16, v44
	v_fma_f32 v22, v22, v54, v71
	v_and_b32_e32 v71, 0xffff0000, v44
	v_fma_f32 v23, v23, v55, v71
	v_lshlrev_b32_e32 v71, 16, v45
	v_fma_f32 v24, v24, v56, v71
	v_and_b32_e32 v71, 0xffff0000, v45
	v_fma_f32 v25, v25, v57, v71
	v_lshlrev_b32_e32 v71, 16, v46
	v_fma_f32 v26, v26, v58, v71
	v_and_b32_e32 v71, 0xffff0000, v46
	v_fma_f32 v27, v27, v59, v71
	v_lshlrev_b32_e32 v71, 16, v47
	v_fma_f32 v28, v28, v60, v71
	v_and_b32_e32 v71, 0xffff0000, v47
	v_fma_f32 v29, v29, v61, v71
	v_lshlrev_b32_e32 v71, 16, v48
	v_fma_f32 v30, v30, v62, v71
	v_and_b32_e32 v71, 0xffff0000, v48
	v_fma_f32 v31, v31, v63, v71
	v_lshlrev_b32_e32 v71, 16, v49
	v_fma_f32 v32, v32, v64, v71
	v_and_b32_e32 v71, 0xffff0000, v49
	v_fma_f32 v33, v33, v65, v71

; __device__ __forceinline__ unsigned f2bf(float f) { return cvt_pk_bf16(f, 0.f) & 0xffffu; }
; __device__ __forceinline__ void hgrn_m3(Frame& F) {
;     ...
;         float cs[16]; float run = 0.f;
; #pragma unroll
;         for (int j = 0; j < 16; ++j) { run += gg[j]; cs[j] = run; }
;         Tl[i * 128 + k] = run;
;     ...
;         __syncthreads();
; #pragma unroll
;         for (int r = 0; r < 4; ++r) {
;             const int t = 16 * wi + 4 * g + r;
;             const float tot = SS[t] + SS[64 + t];
;             const float rstd = 1.0f / sqrtf(tot * (1.0f / 128.0f) + RMS_EPS);
; #pragma unroll
;             for (int vt = 0; vt < 4; ++vt) HB[(t0 + t) * D + 128 * h + 64 * vh + 16 * vt + c16] = (unsigned short)f2bf(o[vt][r] * rstd * bf2f(gv[vt][r]));
.LBB0_444:
	s_or_b64 exec, exec, s[24:25]
	s_waitcnt vmcnt(0)
	v_lshlrev_b32_e32 v194, 16, v79
	v_add_f32_e32 v195, 0, v194
	v_lshlrev_b32_e32 v194, 16, v89
	v_add_f32_e32 v195, v195, v194
	v_lshlrev_b32_e32 v194, 16, v101
	v_add_f32_e32 v195, v195, v194
	v_lshlrev_b32_e32 v194, 16, v104
	v_add_f32_e32 v195, v195, v194
	v_lshlrev_b32_e32 v194, 16, v107
	v_add_f32_e32 v195, v195, v194
	v_lshlrev_b32_e32 v194, 16, v110
	v_add_f32_e32 v195, v195, v194
	v_lshlrev_b32_e32 v194, 16, v112
	v_add_f32_e32 v195, v195, v194
	v_lshlrev_b32_e32 v194, 16, v117
	v_add_f32_e32 v195, v195, v194
	v_lshlrev_b32_e32 v194, 16, v118
	v_add_f32_e32 v195, v195, v194
	v_lshlrev_b32_e32 v194, 16, v122
	v_add_f32_e32 v195, v195, v194
	v_lshlrev_b32_e32 v194, 16, v125
	v_add_f32_e32 v195, v195, v194
	v_lshlrev_b32_e32 v194, 16, v130
	v_add_f32_e32 v195, v195, v194
	v_lshlrev_b32_e32 v194, 16, v135
	v_add_f32_e32 v195, v195, v194
	v_lshlrev_b32_e32 v194, 16, v148
	v_add_f32_e32 v195, v195, v194
	v_lshlrev_b32_e32 v194, 16, v153
	v_add_f32_e32 v195, v195, v194
	v_lshlrev_b32_e32 v194, 16, v172
	v_add_f32_e32 v195, v195, v194
	ds_write_b32 v128, v195
	s_waitcnt lgkmcnt(0)
	s_barrier
	ds_read_b128 v[50:53], v151
	ds_read_b128 v[54:57], v151 offset:256
	s_add_i32 s77, s77, 1
	s_add_i32 s86, s86, 64
	s_cmp_eq_u32 s77, 16
	s_waitcnt lgkmcnt(0)
	v_add_f32_e32 v50, v50, v54
	v_fmamk_f32 v50, v50, 0x3c000000, v252
	v_mul_f32_e32 v54, 0x4f800000, v50
	v_cmp_gt_f32_e32 vcc, s85, v50
	s_nop 1
	v_cndmask_b32_e32 v50, v50, v54, vcc
	v_sqrt_f32_e32 v54, v50
	s_nop 0
	v_add_u32_e32 v58, -1, v54
	v_fma_f32 v60, -v58, v54, v50
	v_add_u32_e32 v59, 1, v54
	v_cmp_ge_f32_e64 s[62:63], 0, v60
	s_nop 1
	v_cndmask_b32_e64 v58, v54, v58, s[62:63]
	v_fma_f32 v54, -v59, v54, v50
	v_cmp_lt_f32_e64 s[62:63], 0, v54
	s_nop 1
	v_cndmask_b32_e64 v54, v58, v59, s[62:63]
	v_mul_f32_e32 v58, 0x37800000, v54
	v_cndmask_b32_e32 v54, v54, v58, vcc
	v_cmp_class_f32_e32 vcc, v50, v220
	s_nop 1
	v_cndmask_b32_e32 v50, v54, v50, vcc
	v_div_scale_f32 v54, s[24:25], v50, v50, 1.0
	v_rcp_f32_e32 v58, v54
	s_nop 0
	v_fma_f32 v59, -v54, v58, 1.0
	v_fmac_f32_e32 v58, v59, v58
	v_div_scale_f32 v59, vcc, 1.0, v50, 1.0
	v_mul_f32_e32 v60, v59, v58
	v_fma_f32 v61, -v54, v60, v59
	v_fmac_f32_e32 v60, v61, v58
	v_fma_f32 v54, -v54, v60, v59
	v_div_fmas_f32 v54, v54, v58, v60
	v_div_fixup_f32 v50, v54, v50, 1.0
	v_mul_f32_e32 v34, v34, v50
	s_waitcnt vmcnt(15)
	v_lshlrev_b32_e32 v54, 16, v187
	v_lshlrev_b64 v[58:59], 11, v[98:99]
	v_mul_f32_e32 v34, v34, v54
	v_lshl_add_u64 v[58:59], v[96:97], 0, v[58:59]
	v_cvt_pk_bf16_f32 v34, v34, s0
	global_store_short v[58:59], v34, off
	v_mul_f32_e32 v34, v38, v50
	s_waitcnt vmcnt(14)
	v_lshlrev_b32_e32 v38, 16, v186
	v_mul_f32_e32 v34, v34, v38
	v_cvt_pk_bf16_f32 v34, v34, s0
	global_store_short v[58:59], v34, off offset:32
	v_mul_f32_e32 v34, v42, v50
	s_waitcnt vmcnt(13)
	v_lshlrev_b32_e32 v38, 16, v185
	v_mul_f32_e32 v34, v34, v38
	v_add_f32_e32 v38, v51, v55
	v_fmamk_f32 v38, v38, 0x3c000000, v252
	v_mul_f32_e32 v42, 0x4f800000, v38
	v_cmp_gt_f32_e32 vcc, s85, v38
	v_cvt_pk_bf16_f32 v34, v34, s0
	global_store_short v[58:59], v34, off offset:64
	v_cndmask_b32_e32 v38, v38, v42, vcc
	v_sqrt_f32_e32 v42, v38
	v_mul_f32_e32 v34, v46, v50
	s_waitcnt vmcnt(11)
	v_lshlrev_b32_e32 v46, 16, v184
	v_mul_f32_e32 v34, v34, v46
	v_add_u32_e32 v50, -1, v42
	v_fma_f32 v51, -v50, v42, v38
	v_cmp_ge_f32_e64 s[62:63], 0, v51
	v_add_u32_e32 v51, 1, v42
	v_cvt_pk_bf16_f32 v34, v34, s0
	v_cndmask_b32_e64 v50, v42, v50, s[62:63]
	v_fma_f32 v42, -v51, v42, v38
	v_cmp_lt_f32_e64 s[62:63], 0, v42
	global_store_short v[58:59], v34, off offset:96
	s_nop 0
	v_cndmask_b32_e64 v42, v50, v51, s[62:63]
	v_mul_f32_e32 v50, 0x37800000, v42
	v_cndmask_b32_e32 v42, v42, v50, vcc
	v_cmp_class_f32_e32 vcc, v38, v220
	s_nop 1
	v_cndmask_b32_e32 v38, v42, v38, vcc
	v_div_scale_f32 v42, s[24:25], v38, v38, 1.0
	v_rcp_f32_e32 v50, v42
	s_nop 0
	v_fma_f32 v34, -v42, v50, 1.0
	v_fmac_f32_e32 v50, v34, v50
	v_div_scale_f32 v34, vcc, 1.0, v38, 1.0
	v_mul_f32_e32 v46, v34, v50
	v_fma_f32 v51, -v42, v46, v34
	v_fmac_f32_e32 v46, v51, v50
	v_fma_f32 v34, -v42, v46, v34
	v_div_fmas_f32 v34, v34, v50, v46
	v_div_fixup_f32 v34, v34, v38, 1.0
	v_mov_b32_e32 v51, s26
	v_or_b32_e32 v50, s7, v84
	v_mul_f32_e32 v35, v35, v34
	v_lshlrev_b32_e32 v38, 16, v183
	v_lshlrev_b64 v[50:51], 11, v[50:51]
	v_mul_f32_e32 v35, v35, v38
	v_lshl_add_u64 v[50:51], v[96:97], 0, v[50:51]
	v_cvt_pk_bf16_f32 v35, v35, s0
	global_store_short v[50:51], v35, off
	v_mul_f32_e32 v35, v39, v34
	v_lshlrev_b32_e32 v38, 16, v182
	v_mul_f32_e32 v35, v35, v38
	v_cvt_pk_bf16_f32 v35, v35, s0
	global_store_short v[50:51], v35, off offset:32
	v_mul_f32_e32 v35, v43, v34
	v_lshlrev_b32_e32 v38, 16, v181
	v_mul_f32_e32 v35, v35, v38
	v_add_f32_e32 v38, v52, v56
	v_fmamk_f32 v38, v38, 0x3c000000, v252
	v_mul_f32_e32 v39, 0x4f800000, v38
	v_cmp_gt_f32_e32 vcc, s85, v38
	v_cvt_pk_bf16_f32 v35, v35, s0
	global_store_short v[50:51], v35, off offset:64
	v_cndmask_b32_e32 v38, v38, v39, vcc
	v_sqrt_f32_e32 v39, v38
	v_mul_f32_e32 v34, v47, v34
	v_lshlrev_b32_e32 v35, 16, v180
	v_mul_f32_e32 v34, v34, v35
	v_add_u32_e32 v42, -1, v39
	v_fma_f32 v43, -v42, v39, v38
	v_cmp_ge_f32_e64 s[62:63], 0, v43
	v_add_u32_e32 v43, 1, v39
	v_cvt_pk_bf16_f32 v34, v34, s0
	v_cndmask_b32_e64 v42, v39, v42, s[62:63]
	v_fma_f32 v39, -v43, v39, v38
	v_cmp_lt_f32_e64 s[62:63], 0, v39
	global_store_short v[50:51], v34, off offset:96
	s_nop 0
	v_cndmask_b32_e64 v39, v42, v43, s[62:63]
	v_mul_f32_e32 v42, 0x37800000, v39
	v_cndmask_b32_e32 v39, v39, v42, vcc
	v_cmp_class_f32_e32 vcc, v38, v220
	s_nop 1
	v_cndmask_b32_e32 v38, v39, v38, vcc
	v_div_scale_f32 v39, s[24:25], v38, v38, 1.0
	v_rcp_f32_e32 v42, v39
	s_nop 0
	v_fma_f32 v34, -v39, v42, 1.0
	v_fmac_f32_e32 v42, v34, v42
	v_div_scale_f32 v34, vcc, 1.0, v38, 1.0
	v_mul_f32_e32 v35, v34, v42
	v_fma_f32 v43, -v39, v35, v34
	v_fmac_f32_e32 v35, v43, v42
	v_fma_f32 v34, -v39, v35, v34
	v_div_fmas_f32 v34, v34, v42, v35
	v_div_fixup_f32 v38, v34, v38, 1.0
	v_mov_b32_e32 v35, s26
	v_or_b32_e32 v34, s7, v86
	v_mul_f32_e32 v36, v36, v38
	s_waitcnt vmcnt(15)
; __device__ __forceinline__ unsigned f2bf(float f) { return cvt_pk_bf16(f, 0.f) & 0xffffu; }
; __device__ __forceinline__ void hgrn_m3(Frame& F) {
;     ...
;         float cs[16]; float run = 0.f;
; #pragma unroll
;         for (int j = 0; j < 16; ++j) { run += gg[j]; cs[j] = run; }
;         Tl[i * 128 + k] = run;
;         __syncthreads();
;         const float T0 = Tl[k], T1 = Tl[128 + k], T2 = Tl[256 + k], T3 = Tl[384 + k];
;         const float Bi = (i == 0) ? 0.f : (i == 1) ? T0 : (i == 2) ? (T0 + T1) : (T0 + T1 + T2);
;     ...
;         for (int r = 0; r < 4; ++r) {
;             const int t = 16 * wi + 4 * g + r;
;             const float tot = SS[t] + SS[64 + t];
;             const float rstd = 1.0f / sqrtf(tot * (1.0f / 128.0f) + RMS_EPS);
; #pragma unroll
;             for (int vt = 0; vt < 4; ++vt) HB[(t0 + t) * D + 128 * h + 64 * vh + 16 * vt + c16] = (unsigned short)f2bf(o[vt][r] * rstd * bf2f(gv[vt][r]));
	v_lshlrev_b32_e32 v39, 16, v179
	v_lshlrev_b64 v[34:35], 11, v[34:35]
	v_mul_f32_e32 v36, v36, v39
	v_lshl_add_u64 v[34:35], v[96:97], 0, v[34:35]
	v_cvt_pk_bf16_f32 v36, v36, s0
	global_store_short v[34:35], v36, off
	v_mul_f32_e32 v36, v40, v38
	s_waitcnt vmcnt(14)
	v_lshlrev_b32_e32 v39, 16, v178
	v_mul_f32_e32 v36, v36, v39
	v_cvt_pk_bf16_f32 v36, v36, s0
	global_store_short v[34:35], v36, off offset:32
	v_mul_f32_e32 v36, v44, v38
	s_waitcnt vmcnt(13)
	v_lshlrev_b32_e32 v39, 16, v177
	v_mul_f32_e32 v36, v36, v39
	v_add_f32_e32 v39, v53, v57
	v_fmamk_f32 v39, v39, 0x3c000000, v252
	v_mul_f32_e32 v40, 0x4f800000, v39
	v_cmp_gt_f32_e32 vcc, s85, v39
	v_cvt_pk_bf16_f32 v36, v36, s0
	global_store_short v[34:35], v36, off offset:64
	v_cndmask_b32_e32 v39, v39, v40, vcc
	v_sqrt_f32_e32 v40, v39
	v_mul_f32_e32 v36, v48, v38
	s_waitcnt vmcnt(11)
	v_lshlrev_b32_e32 v38, 16, v176
	v_mul_f32_e32 v36, v36, v38
	v_add_u32_e32 v42, -1, v40
	v_fma_f32 v43, -v42, v40, v39
	v_cmp_ge_f32_e64 s[62:63], 0, v43
	v_add_u32_e32 v43, 1, v40
	v_cvt_pk_bf16_f32 v36, v36, s0
	v_cndmask_b32_e64 v42, v40, v42, s[62:63]
	v_fma_f32 v40, -v43, v40, v39
	v_cmp_lt_f32_e64 s[62:63], 0, v40
	global_store_short v[34:35], v36, off offset:96
	v_lshlrev_b32_e32 v38, 16, v175
	v_cndmask_b32_e64 v40, v42, v43, s[62:63]
	v_mul_f32_e32 v42, 0x37800000, v40
	v_cndmask_b32_e32 v40, v40, v42, vcc
	v_cmp_class_f32_e32 vcc, v39, v220
	s_nop 1
	v_cndmask_b32_e32 v39, v40, v39, vcc
	v_div_scale_f32 v40, s[24:25], v39, v39, 1.0
	v_rcp_f32_e32 v42, v40
	s_nop 0
	v_fma_f32 v34, -v40, v42, 1.0
	v_fmac_f32_e32 v42, v34, v42
	v_div_scale_f32 v34, vcc, 1.0, v39, 1.0
	v_mul_f32_e32 v35, v34, v42
	v_fma_f32 v36, -v40, v35, v34
	v_fmac_f32_e32 v35, v36, v42
	v_fma_f32 v34, -v40, v35, v34
	v_div_fmas_f32 v34, v34, v42, v35
	v_div_fixup_f32 v36, v34, v39, 1.0
	v_mov_b32_e32 v35, s26
	v_or_b32_e32 v34, s7, v88
	v_mul_f32_e32 v37, v37, v36
	v_lshlrev_b64 v[34:35], 11, v[34:35]
	v_mul_f32_e32 v37, v37, v38
	v_lshl_add_u64 v[34:35], v[96:97], 0, v[34:35]
	v_cvt_pk_bf16_f32 v37, v37, s0
	global_store_short v[34:35], v37, off
	v_mul_f32_e32 v37, v41, v36
	v_lshlrev_b32_e32 v38, 16, v174
	v_mul_f32_e32 v37, v37, v38
	v_cvt_pk_bf16_f32 v37, v37, s0
	global_store_short v[34:35], v37, off offset:32
	v_mul_f32_e32 v37, v45, v36
	v_lshlrev_b32_e32 v38, 16, v93
	v_mul_f32_e32 v37, v37, v38
	v_cvt_pk_bf16_f32 v37, v37, s0
	global_store_short v[34:35], v37, off offset:64
	v_mul_f32_e32 v36, v49, v36
	v_lshlrev_b32_e32 v37, 16, v91
	v_mul_f32_e32 v36, v36, v37
	v_cvt_pk_bf16_f32 v36, v36, s0
	global_store_short v[34:35], v36, off offset:96
	s_cbranch_scc1 .LBB0_442
.LBB0_445:
	v_lshlrev_b32_e32 v57, 16, v79
	v_lshlrev_b32_e32 v56, 16, v89
	v_add_f32_e32 v34, 0, v57
	v_lshlrev_b32_e32 v55, 16, v101
	v_add_f32_e32 v34, v34, v56
	v_lshlrev_b32_e32 v54, 16, v104
	v_add_f32_e32 v34, v34, v55
	v_lshlrev_b32_e32 v49, 16, v107
	v_add_f32_e32 v34, v34, v54
	v_lshlrev_b32_e32 v48, 16, v110
	v_add_f32_e32 v34, v34, v49
	v_lshlrev_b32_e32 v47, 16, v112
	v_add_f32_e32 v34, v34, v48
	v_lshlrev_b32_e32 v41, 16, v117
	v_add_f32_e32 v34, v34, v47
	v_lshlrev_b32_e32 v42, 16, v118
	v_add_f32_e32 v34, v34, v41
	v_lshlrev_b32_e32 v43, 16, v122
	v_add_f32_e32 v34, v34, v42
	v_lshlrev_b32_e32 v44, 16, v125
	v_add_f32_e32 v34, v34, v43
	v_lshlrev_b32_e32 v46, 16, v130
	v_add_f32_e32 v34, v34, v44
	v_lshlrev_b32_e32 v45, 16, v135
	v_add_f32_e32 v34, v34, v46
	v_lshlrev_b32_e32 v40, 16, v148
	v_add_f32_e32 v34, v34, v45
	v_lshlrev_b32_e32 v39, 16, v153
	v_add_f32_e32 v34, v34, v40
	v_lshlrev_b32_e32 v38, 16, v172
	v_add_f32_e32 v34, v34, v39
	v_add_f32_e32 v52, v34, v38
	s_cmp_eq_u32 s101, 0
	s_cbranch_scc0 .Lmy_m3_tl_done
	ds_write_b32 v128, v52
	s_waitcnt lgkmcnt(0)
	s_barrier
	s_mov_b32 s101, 1
.Lmy_m3_tl_done:
	ds_read2st64_b32 v[36:37], v129 offset1:2
	ds_read2st64_b32 v[34:35], v129 offset0:4 offset1:6
	v_readfirstlane_b32 s24, v72
	s_cmp_eq_u32 s24, 0
	s_cbranch_scc1 .Lmy_m3_c0
	s_cmp_eq_u32 s24, 1
	s_cbranch_scc1 .Lmy_m3_c1
	s_cmp_eq_u32 s24, 2
	s_cbranch_scc1 .Lmy_m3_c2
	v_mov_b32_e32 v53, 0
	s_waitcnt lgkmcnt(1)
	v_add_f32_e32 v50, v36, v37
	s_waitcnt lgkmcnt(0)
	v_add_f32_e32 v53, v50, v34
	s_waitcnt lgkmcnt(0)
	v_cndmask_b32_e64 v50, 0, v35, s[40:41]
	s_waitcnt lgkmcnt(0)
	v_add_f32_e32 v35, v37, v34
	v_mul_f32_e32 v35, 0x3fb8aa3b, v35
	v_exp_f32_e32 v51, v35
	s_waitcnt lgkmcnt(0)
; #define LAS __attribute__((address_space(3)))
; __device__ __forceinline__ unsigned pk2(float lo, float hi) { return cvt_pk_bf16(lo, hi); }
; __device__ __forceinline__ unsigned f2bf(float f) { return cvt_pk_bf16(f, 0.f) & 0xffffu; }
; __device__ __forceinline__ void hgrn_m3(Frame& F) {
;     ...
;         const float Gi = __expf((i == 0) ? (T1 + T2 + T3) : (i == 1) ? (T2 + T3) : (i == 2) ? T3 : 0.f);
;         if (i == 0) Dl[k] = __expf(T0 + T1 + T2 + T3);
;         const float eB = __expf(Bi);
;         float Fq[4];
;         Fq[0] = (i == 0) ? __expf(fminf(-run, 80.f)) : (i == 1) ? 1.0f : (i == 2) ? __expf(T1) : __expf(T1 + T2);
;         Fq[1] = (i == 1) ? __expf(fminf(-run, 80.f)) : (i == 2) ? 1.0f : __expf(T2);
;         Fq[2] = (i == 2) ? __expf(fminf(-run, 80.f)) : 1.0f;
;         Fq[3] = __expf(fminf(-run, 80.f));
;         const int blk0 = (i * (i + 1)) >> 1;
;         unsigned vw[8], kw[8];
;         float fj[16], e1a[16], e2a[16];
; #pragma unroll
;         for (int j = 0; j < 16; ++j) fj[j] = __expf(gg[j]);
;         { float p = 1.0f;
; #pragma unroll
;           for (int j = 0; j < 16; ++j) { p *= fj[j]; e1a[j] = p; }
;           p = 1.0f;
; #pragma unroll
;           for (int j = 15; j >= 0; --j) { e2a[j] = p; p *= fj[j]; } }
; #pragma unroll
;         for (int j = 0; j < 16; ++j) {
;             const float e1 = e1a[j], e2 = e2a[j], kk = 1.0f - fj[j];
;             const float qe = q[j] * e1;
;             *(LAS unsigned short*)(QT + (16 * i + j) * P128 + k * 2) = (unsigned short)f2bf(qe * eB);
;             *(LAS unsigned short*)(KH + (16 * i + j) * P128 + k * 2) = (unsigned short)f2bf(kk * e2);
; #pragma unroll
;             for (int jj = 0; jj < 4; ++jj) if (jj <= i) *(LAS unsigned short*)(QH + (blk0 + jj) * (16 * P128) + j * P128 + k * 2) = (unsigned short)f2bf(qe * Fq[jj]);
;             if (j & 1) { vw[j >> 1] = (unsigned)vr[j - 1] | ((unsigned)vr[j] << 16); kw[j >> 1] = pk2((1.0f - fj[j - 1]) * e2a[j - 1] * Gi, kk * e2 * Gi); }
	v_max_f32_e64 v35, -v52, -v52
	v_min_f32_e32 v35, 0x42a00000, v35
	v_mov_b32_e32 v52, 1.0
	v_mul_f32_e32 v34, 0x3fb8aa3b, v34
	v_exp_f32_e32 v52, v34
	v_mul_f32_e32 v49, 0x3fb8aa3b, v49
	v_mul_f32_e32 v48, 0x3fb8aa3b, v48
	v_mul_f32_e32 v39, 0x3fb8aa3b, v39
	v_mul_f32_e32 v38, 0x3fb8aa3b, v38
	v_mul_f32_e32 v36, 0x3fb8aa3b, v57
	v_exp_f32_e32 v65, v49
	v_exp_f32_e32 v64, v48
	v_mul_f32_e32 v40, 0x3fb8aa3b, v40
	v_exp_f32_e32 v48, v39
	v_exp_f32_e32 v49, v38
	v_exp_f32_e32 v70, v36
	v_mul_f32_e32 v36, 0x3fb8aa3b, v56
	v_mul_f32_e32 v45, 0x3fb8aa3b, v45
	v_exp_f32_e32 v56, v40
	v_mul_f32_e32 v46, 0x3fb8aa3b, v46
	v_exp_f32_e32 v57, v45
	v_mul_f32_e32 v47, 0x3fb8aa3b, v47
	v_mul_f32_e32 v44, 0x3fb8aa3b, v44
	v_exp_f32_e32 v58, v46
	v_exp_f32_e32 v63, v47
	v_mul_f32_e32 v43, 0x3fb8aa3b, v43
	v_exp_f32_e32 v44, v44
	v_mul_f32_e32 v47, v48, v49
	v_mul_f32_e32 v42, 0x3fb8aa3b, v42
	v_exp_f32_e32 v43, v43
	v_mul_f32_e32 v46, v56, v47
	v_mul_f32_e32 v41, 0x3fb8aa3b, v41
	v_exp_f32_e32 v42, v42
	v_mul_f32_e32 v45, v57, v46
	v_exp_f32_e32 v41, v41
	v_mul_f32_e32 v59, v58, v45
	v_mul_f32_e32 v60, v44, v59
	v_mul_f32_e32 v61, v43, v60
	v_mul_f32_e32 v37, 0x3fb8aa3b, v54
	v_mul_f32_e32 v62, v42, v61
	v_mul_f32_e32 v34, 0x3fb8aa3b, v53
	v_exp_f32_e32 v71, v36
	v_mul_f32_e32 v36, 0x3fb8aa3b, v55
	v_exp_f32_e32 v37, v37
	v_mul_f32_e32 v40, v41, v62
	v_exp_f32_e32 v53, v34
	v_exp_f32_e32 v36, v36
	v_mul_f32_e32 v39, v63, v40
	v_mul_f32_e32 v38, v64, v39
	v_lshlrev_b32_e32 v34, 16, v85
	v_mul_f32_e32 v68, v65, v38
	v_mul_f32_e32 v69, v37, v68
	v_mul_f32_e32 v93, v70, v34
	v_mul_f32_e32 v91, v36, v69
	v_mul_f32_e32 v34, v93, v53
	v_mul_f32_e32 v54, v71, v91
	v_sub_f32_e32 v55, 1.0, v70
	v_cvt_pk_bf16_f32 v34, v34, s0
	ds_write_b16 v166, v34
	v_mul_f32_e32 v34, v55, v54
	v_cvt_pk_bf16_f32 v54, v34, s0
	ds_write_b16 v166, v54 offset:60928
	v_mul_f32_e32 v54, v93, v51
	v_cvt_pk_bf16_f32 v54, v54, s0
	ds_write_b16 v82, v54 offset:17408
	v_mul_f32_e32 v54, v93, v52
	v_cvt_pk_bf16_f32 v54, v54, s0
	ds_write_b16 v82, v54 offset:21760
	v_mul_f32_e32 v35, 0x3fb8aa3b, v35
	v_exp_f32_e32 v54, v35
	s_nop 0
	v_cndmask_b32_e64 v55, 1.0, v54, s[40:41]
	v_mul_f32_e32 v35, v93, v55
	v_cvt_pk_bf16_f32 v35, v35, s0
	ds_write_b16 v82, v35 offset:26112
	v_mul_f32_e32 v35, v93, v54
	v_cvt_pk_bf16_f32 v35, v35, s0
	ds_write_b16 v82, v35 offset:30464
	v_mul_f32_e32 v70, v70, v71
	v_lshlrev_b32_e32 v35, 16, v95
	v_sub_f32_e32 v93, 1.0, v71
	v_mul_f32_e32 v71, v70, v35
	v_mul_f32_e32 v35, v71, v53
	v_cvt_pk_bf16_f32 v35, v35, s0
	ds_write_b16 v166, v35 offset:272
	v_mul_f32_e32 v35, v93, v91
	v_cvt_pk_bf16_f32 v91, v35, s0
	ds_write_b16 v166, v91 offset:61200
	v_mul_f32_e32 v91, v71, v51
	v_cvt_pk_bf16_f32 v91, v91, s0
	ds_write_b16 v82, v91 offset:17680
	v_mul_f32_e32 v91, v71, v52
	v_cvt_pk_bf16_f32 v91, v91, s0
	ds_write_b16 v82, v91 offset:22032
	v_mul_f32_e32 v91, v71, v55
	v_cvt_pk_bf16_f32 v91, v91, s0
	ds_write_b16 v82, v91 offset:26384
	v_mul_f32_e32 v71, v71, v54
	v_cvt_pk_bf16_f32 v71, v71, s0
	ds_write_b16 v82, v71 offset:30736
	v_mul_f32_e32 v70, v70, v36
	v_lshlrev_b32_e32 v71, 16, v103
	v_sub_f32_e32 v36, 1.0, v36
	v_mul_f32_e32 v71, v70, v71
	v_mul_f32_e32 v91, v71, v53
	v_mul_f32_e32 v36, v36, v69
	v_cvt_pk_bf16_f32 v91, v91, s0
	v_cvt_pk_bf16_f32 v69, v36, s0
	ds_write_b16 v166, v91 offset:544
	ds_write_b16 v166, v69 offset:61472
	v_mul_f32_e32 v69, v71, v51
	v_cvt_pk_bf16_f32 v69, v69, s0
	ds_write_b16 v82, v69 offset:17952
	v_mul_f32_e32 v69, v71, v52
	v_cvt_pk_bf16_f32 v69, v69, s0
	ds_write_b16 v82, v69 offset:22304
	v_mul_f32_e32 v69, v71, v55
	v_cvt_pk_bf16_f32 v69, v69, s0
	ds_write_b16 v82, v69 offset:26656
	v_mul_f32_e32 v69, v71, v54
	v_cvt_pk_bf16_f32 v69, v69, s0
	ds_write_b16 v82, v69 offset:31008
	v_mul_f32_e32 v69, v70, v37
	v_lshlrev_b32_e32 v70, 16, v105
	v_sub_f32_e32 v37, 1.0, v37
	v_mul_f32_e32 v70, v69, v70
	v_mul_f32_e32 v71, v70, v53
	v_mul_f32_e32 v37, v37, v68
	v_cvt_pk_bf16_f32 v71, v71, s0
	v_cvt_pk_bf16_f32 v68, v37, s0
	ds_write_b16 v166, v71 offset:816
	ds_write_b16 v166, v68 offset:61744
	v_mul_f32_e32 v68, v70, v51
	v_cvt_pk_bf16_f32 v68, v68, s0
	ds_write_b16 v82, v68 offset:18224
	v_mul_f32_e32 v68, v70, v52
	v_cvt_pk_bf16_f32 v68, v68, s0
	ds_write_b16 v82, v68 offset:22576
	v_mul_f32_e32 v68, v70, v55
	v_cvt_pk_bf16_f32 v68, v68, s0
	ds_write_b16 v82, v68 offset:26928
	v_mul_f32_e32 v68, v54, v70
	v_cvt_pk_bf16_f32 v68, v68, s0
	ds_write_b16 v82, v68 offset:31280
	v_mul_f32_e32 v68, v69, v65
	v_lshlrev_b32_e32 v69, 16, v108
	v_sub_f32_e32 v70, 1.0, v65
	v_mul_f32_e32 v65, v68, v69
	v_mul_f32_e32 v69, v65, v53
	v_cvt_pk_bf16_f32 v69, v69, s0
	v_mul_f32_e32 v38, v70, v38
	ds_write_b16 v166, v69 offset:1088
	v_cvt_pk_bf16_f32 v69, v38, s0
	ds_write_b16 v166, v69 offset:62016
	v_mul_f32_e32 v69, v65, v51
	v_cvt_pk_bf16_f32 v69, v69, s0
	ds_write_b16 v82, v69 offset:18496
	v_mul_f32_e32 v69, v65, v52
	v_cvt_pk_bf16_f32 v69, v69, s0
	ds_write_b16 v82, v69 offset:22848
	v_mul_f32_e32 v69, v55, v65
	v_cvt_pk_bf16_f32 v69, v69, s0
	ds_write_b16 v82, v69 offset:27200
	v_mul_f32_e32 v65, v54, v65
	v_cvt_pk_bf16_f32 v65, v65, s0
	ds_write_b16 v82, v65 offset:31552
	v_mul_f32_e32 v65, v68, v64
	v_lshlrev_b32_e32 v68, 16, v111
	v_sub_f32_e32 v69, 1.0, v64
	v_mul_f32_e32 v64, v65, v68
	v_mul_f32_e32 v68, v64, v53
	v_cvt_pk_bf16_f32 v68, v68, s0
	v_mul_f32_e32 v39, v69, v39
	ds_write_b16 v166, v68 offset:1360
	v_cvt_pk_bf16_f32 v68, v39, s0
	ds_write_b16 v166, v68 offset:62288
	v_mul_f32_e32 v68, v64, v51
	v_cvt_pk_bf16_f32 v68, v68, s0
	ds_write_b16 v82, v68 offset:18768
	v_mul_f32_e32 v68, v64, v52
	v_cvt_pk_bf16_f32 v68, v68, s0
; #define LAS __attribute__((address_space(3)))
; __device__ __forceinline__ unsigned pk2(float lo, float hi) { return cvt_pk_bf16(lo, hi); }
; __device__ __forceinline__ unsigned f2bf(float f) { return cvt_pk_bf16(f, 0.f) & 0xffffu; }
; __device__ __forceinline__ void hgrn_m3(Frame& F) {
;     ...
;         for (int j = 0; j < 16; ++j) {
;             const float e1 = e1a[j], e2 = e2a[j], kk = 1.0f - fj[j];
;             const float qe = q[j] * e1;
;             *(LAS unsigned short*)(QT + (16 * i + j) * P128 + k * 2) = (unsigned short)f2bf(qe * eB);
;             *(LAS unsigned short*)(KH + (16 * i + j) * P128 + k * 2) = (unsigned short)f2bf(kk * e2);
; #pragma unroll
;             for (int jj = 0; jj < 4; ++jj) if (jj <= i) *(LAS unsigned short*)(QH + (blk0 + jj) * (16 * P128) + j * P128 + k * 2) = (unsigned short)f2bf(qe * Fq[jj]);
;             if (j & 1) { vw[j >> 1] = (unsigned)vr[j - 1] | ((unsigned)vr[j] << 16); kw[j >> 1] = pk2((1.0f - fj[j - 1]) * e2a[j - 1] * Gi, kk * e2 * Gi); }
;         }
	ds_write_b16 v82, v68 offset:23120
	v_mul_f32_e32 v68, v55, v64
	v_cvt_pk_bf16_f32 v68, v68, s0
	ds_write_b16 v82, v68 offset:27472
	v_mul_f32_e32 v64, v54, v64
	v_cvt_pk_bf16_f32 v64, v64, s0
	ds_write_b16 v82, v64 offset:31824
	v_mul_f32_e32 v64, v65, v63
	v_lshlrev_b32_e32 v65, 16, v114
	v_sub_f32_e32 v68, 1.0, v63
	v_mul_f32_e32 v63, v64, v65
	v_mul_f32_e32 v65, v63, v53
	v_cvt_pk_bf16_f32 v65, v65, s0
	v_mul_f32_e32 v40, v68, v40
	ds_write_b16 v166, v65 offset:1632
	v_cvt_pk_bf16_f32 v65, v40, s0
	ds_write_b16 v166, v65 offset:62560
	v_mul_f32_e32 v65, v63, v51
	v_cvt_pk_bf16_f32 v65, v65, s0
	ds_write_b16 v82, v65 offset:19040
	v_mul_f32_e32 v65, v63, v52
	v_cvt_pk_bf16_f32 v65, v65, s0
	ds_write_b16 v82, v65 offset:23392
	v_mul_f32_e32 v65, v55, v63
	v_cvt_pk_bf16_f32 v65, v65, s0
	ds_write_b16 v82, v65 offset:27744
	v_mul_f32_e32 v63, v54, v63
	v_cvt_pk_bf16_f32 v63, v63, s0
	ds_write_b16 v82, v63 offset:32096
	v_mul_f32_e32 v63, v64, v41
	v_lshlrev_b32_e32 v64, 16, v119
	v_sub_f32_e32 v41, 1.0, v41
	v_mul_f32_e32 v64, v63, v64
	v_mul_f32_e32 v65, v64, v53
	v_mul_f32_e32 v41, v41, v62
	v_cvt_pk_bf16_f32 v65, v65, s0
	v_cvt_pk_bf16_f32 v62, v41, s0
	ds_write_b16 v166, v65 offset:1904
	ds_write_b16 v166, v62 offset:62832
	v_mul_f32_e32 v62, v64, v51
	v_cvt_pk_bf16_f32 v62, v62, s0
	ds_write_b16 v82, v62 offset:19312
	v_mul_f32_e32 v62, v64, v52
	v_cvt_pk_bf16_f32 v62, v62, s0
	ds_write_b16 v82, v62 offset:23664
	v_mul_f32_e32 v62, v55, v64
	v_cvt_pk_bf16_f32 v62, v62, s0
	ds_write_b16 v82, v62 offset:28016
	v_mul_f32_e32 v62, v54, v64
	v_cvt_pk_bf16_f32 v62, v62, s0
	ds_write_b16 v82, v62 offset:32368
	v_mul_f32_e32 v62, v63, v42
	v_lshlrev_b32_e32 v63, 16, v120
	v_sub_f32_e32 v42, 1.0, v42
	v_mul_f32_e32 v63, v62, v63
	v_mul_f32_e32 v64, v63, v53
	v_mul_f32_e32 v42, v42, v61
	v_cvt_pk_bf16_f32 v64, v64, s0
	v_cvt_pk_bf16_f32 v61, v42, s0
	ds_write_b16 v166, v64 offset:2176
	ds_write_b16 v166, v61 offset:63104
	v_mul_f32_e32 v61, v63, v51
	v_cvt_pk_bf16_f32 v61, v61, s0
	ds_write_b16 v82, v61 offset:19584
	v_mul_f32_e32 v61, v63, v52
	v_cvt_pk_bf16_f32 v61, v61, s0
	ds_write_b16 v82, v61 offset:23936
	v_mul_f32_e32 v61, v55, v63
	v_cvt_pk_bf16_f32 v61, v61, s0
	ds_write_b16 v82, v61 offset:28288
	v_mul_f32_e32 v61, v54, v63
	v_cvt_pk_bf16_f32 v61, v61, s0
	ds_write_b16 v82, v61 offset:32640
	v_mul_f32_e32 v61, v62, v43
	v_lshlrev_b32_e32 v62, 16, v123
	v_sub_f32_e32 v43, 1.0, v43
	v_mul_f32_e32 v62, v61, v62
	v_mul_f32_e32 v63, v62, v53
	v_mul_f32_e32 v43, v43, v60
	v_cvt_pk_bf16_f32 v63, v63, s0
	v_cvt_pk_bf16_f32 v60, v43, s0
	ds_write_b16 v166, v63 offset:2448
	ds_write_b16 v166, v60 offset:63376
	v_mul_f32_e32 v60, v62, v51
	v_cvt_pk_bf16_f32 v60, v60, s0
	ds_write_b16 v82, v60 offset:19856
	v_mul_f32_e32 v60, v62, v52
	v_cvt_pk_bf16_f32 v60, v60, s0
	ds_write_b16 v82, v60 offset:24208
	v_mul_f32_e32 v60, v55, v62
	v_cvt_pk_bf16_f32 v60, v60, s0
	ds_write_b16 v82, v60 offset:28560
	v_mul_f32_e32 v60, v54, v62
	v_cvt_pk_bf16_f32 v60, v60, s0
	ds_write_b16 v82, v60 offset:32912
	v_mul_f32_e32 v60, v61, v44
	v_lshlrev_b32_e32 v61, 16, v126
	v_sub_f32_e32 v44, 1.0, v44
	v_mul_f32_e32 v61, v60, v61
	v_mul_f32_e32 v62, v61, v53
	v_mul_f32_e32 v44, v44, v59
	v_cvt_pk_bf16_f32 v62, v62, s0
	v_cvt_pk_bf16_f32 v59, v44, s0
	ds_write_b16 v166, v62 offset:2720
	ds_write_b16 v166, v59 offset:63648
	v_mul_f32_e32 v59, v61, v51
	v_cvt_pk_bf16_f32 v59, v59, s0
	ds_write_b16 v82, v59 offset:20128
	v_mul_f32_e32 v59, v61, v52
	v_cvt_pk_bf16_f32 v59, v59, s0
	ds_write_b16 v82, v59 offset:24480
	v_mul_f32_e32 v59, v55, v61
	v_cvt_pk_bf16_f32 v59, v59, s0
; #define LAS __attribute__((address_space(3)))
; __device__ __forceinline__ unsigned pk2(float lo, float hi) { return cvt_pk_bf16(lo, hi); }
; __device__ __forceinline__ unsigned f2bf(float f) { return cvt_pk_bf16(f, 0.f) & 0xffffu; }
; __device__ __forceinline__ void hgrn_m3(Frame& F) {
;     ...
;         for (int j = 0; j < 16; ++j) {
;             const float e1 = e1a[j], e2 = e2a[j], kk = 1.0f - fj[j];
;             const float qe = q[j] * e1;
;             *(LAS unsigned short*)(QT + (16 * i + j) * P128 + k * 2) = (unsigned short)f2bf(qe * eB);
;             *(LAS unsigned short*)(KH + (16 * i + j) * P128 + k * 2) = (unsigned short)f2bf(kk * e2);
; #pragma unroll
;             for (int jj = 0; jj < 4; ++jj) if (jj <= i) *(LAS unsigned short*)(QH + (blk0 + jj) * (16 * P128) + j * P128 + k * 2) = (unsigned short)f2bf(qe * Fq[jj]);
;             if (j & 1) { vw[j >> 1] = (unsigned)vr[j - 1] | ((unsigned)vr[j] << 16); kw[j >> 1] = pk2((1.0f - fj[j - 1]) * e2a[j - 1] * Gi, kk * e2 * Gi); }
;         }
	ds_write_b16 v82, v59 offset:28832
	v_mul_f32_e32 v59, v54, v61
	v_cvt_pk_bf16_f32 v59, v59, s0
	ds_write_b16 v82, v59 offset:33184
	v_mul_f32_e32 v59, v60, v58
	v_lshlrev_b32_e32 v60, 16, v131
	v_sub_f32_e32 v61, 1.0, v58
	v_mul_f32_e32 v58, v59, v60
	v_mul_f32_e32 v60, v58, v53
	v_cvt_pk_bf16_f32 v60, v60, s0
	v_mul_f32_e32 v45, v61, v45
	ds_write_b16 v166, v60 offset:2992
	v_cvt_pk_bf16_f32 v60, v45, s0
	ds_write_b16 v166, v60 offset:63920
	v_mul_f32_e32 v60, v58, v51
	v_cvt_pk_bf16_f32 v60, v60, s0
	ds_write_b16 v82, v60 offset:20400
	v_mul_f32_e32 v60, v58, v52
	v_cvt_pk_bf16_f32 v60, v60, s0
	ds_write_b16 v82, v60 offset:24752
	v_mul_f32_e32 v60, v55, v58
	v_cvt_pk_bf16_f32 v60, v60, s0
	ds_write_b16 v82, v60 offset:29104
	v_mul_f32_e32 v58, v54, v58
	v_cvt_pk_bf16_f32 v58, v58, s0
	ds_write_b16 v82, v58 offset:33456
	v_mul_f32_e32 v58, v59, v57
	v_lshlrev_b32_e32 v59, 16, v138
	v_sub_f32_e32 v60, 1.0, v57
	v_mul_f32_e32 v57, v58, v59
	v_mul_f32_e32 v59, v57, v53
	v_cvt_pk_bf16_f32 v59, v59, s0
	v_mul_f32_e32 v46, v60, v46
	ds_write_b16 v166, v59 offset:3264
	v_cvt_pk_bf16_f32 v59, v46, s0
	ds_write_b16 v166, v59 offset:64192
	v_mul_f32_e32 v59, v57, v51
	v_cvt_pk_bf16_f32 v59, v59, s0
	ds_write_b16 v82, v59 offset:20672
	v_mul_f32_e32 v59, v57, v52
	v_cvt_pk_bf16_f32 v59, v59, s0
	ds_write_b16 v82, v59 offset:25024
	v_mul_f32_e32 v59, v55, v57
	v_cvt_pk_bf16_f32 v59, v59, s0
	ds_write_b16 v82, v59 offset:29376
	v_mul_f32_e32 v57, v54, v57
	v_cvt_pk_bf16_f32 v57, v57, s0
	ds_write_b16 v82, v57 offset:33728
	v_mul_f32_e32 v57, v58, v56
	v_lshlrev_b32_e32 v58, 16, v149
	v_sub_f32_e32 v59, 1.0, v56
	v_mul_f32_e32 v56, v57, v58
	v_mul_f32_e32 v58, v56, v53
	v_cvt_pk_bf16_f32 v58, v58, s0
	v_mul_f32_e32 v47, v59, v47
	ds_write_b16 v166, v58 offset:3536
	v_cvt_pk_bf16_f32 v58, v47, s0
	ds_write_b16 v166, v58 offset:64464
	v_mul_f32_e32 v58, v56, v51
	v_cvt_pk_bf16_f32 v58, v58, s0
	ds_write_b16 v82, v58 offset:20944
	v_mul_f32_e32 v58, v56, v52
	v_cvt_pk_bf16_f32 v58, v58, s0
	ds_write_b16 v82, v58 offset:25296
	v_mul_f32_e32 v58, v55, v56
	v_cvt_pk_bf16_f32 v58, v58, s0
	ds_write_b16 v82, v58 offset:29648
	v_mul_f32_e32 v56, v54, v56
	v_cvt_pk_bf16_f32 v56, v56, s0
	ds_write_b16 v82, v56 offset:34000
	v_mul_f32_e32 v56, v57, v48
	v_lshlrev_b32_e32 v57, 16, v167
	v_mul_f32_e32 v57, v56, v57
	v_sub_f32_e32 v48, 1.0, v48
	v_mul_f32_e32 v58, v57, v53
	v_cvt_pk_bf16_f32 v58, v58, s0
	v_mul_f32_e32 v48, v49, v48
	ds_write_b16 v166, v58 offset:3808
	v_cvt_pk_bf16_f32 v58, v48, s0
	ds_write_b16 v166, v58 offset:64736
	v_mul_f32_e32 v58, v57, v51
	v_cvt_pk_bf16_f32 v58, v58, s0
	ds_write_b16 v82, v58 offset:21216
	v_mul_f32_e32 v58, v57, v52
	v_cvt_pk_bf16_f32 v58, v58, s0
	ds_write_b16 v82, v58 offset:25568
	v_mul_f32_e32 v58, v55, v57
	v_cvt_pk_bf16_f32 v58, v58, s0
	ds_write_b16 v82, v58 offset:29920
	v_mul_f32_e32 v57, v54, v57
	v_cvt_pk_bf16_f32 v57, v57, s0
	ds_write_b16 v82, v57 offset:34272
	v_mul_f32_e32 v56, v56, v49
	v_lshlrev_b32_e32 v57, 16, v173
	v_mul_f32_e32 v56, v56, v57
	v_mul_f32_e32 v53, v56, v53
	v_sub_f32_e32 v49, 1.0, v49
	v_cvt_pk_bf16_f32 v53, v53, s0
	ds_write_b16 v166, v53 offset:4080
	v_cvt_pk_bf16_f32 v53, v49, s0
	ds_write_b16 v166, v53 offset:65008
	v_mul_f32_e32 v51, v56, v51
	v_cvt_pk_bf16_f32 v51, v51, s0
	ds_write_b16 v82, v51 offset:21488
	v_mul_f32_e32 v51, v56, v52
	v_cvt_pk_bf16_f32 v51, v51, s0
	ds_write_b16 v82, v51 offset:25840
	v_mul_f32_e32 v51, v55, v56
	v_cvt_pk_bf16_f32 v51, v51, s0
	ds_write_b16 v82, v51 offset:30192
	v_mul_f32_e32 v51, v54, v56
	v_cvt_pk_bf16_f32 v51, v51, s0
	ds_write_b16 v82, v51 offset:34544
	s_branch .Lmy_m3_join
